# mod_unit: silu pre-loop batched (36 loads in flight, same silu instruction sequence) on top of the K-loop rewrite
# speedup vs baseline: 1.0089x; 1.0089x over previous
.LBB0_664:
	s_mov_b64 s[4:5], s[0:1]
	v_mov_b32_e32 v37, v254
	s_movk_i32 s6, 0x2400
	s_waitcnt vmcnt(0) lgkmcnt(0)
	v_cmp_gt_i32_e32 vcc, s6, v37
	s_barrier
	s_and_saveexec_b64 s[6:7], vcc
	s_cbranch_execz .LBB0_671
	s_load_dwordx2 s[14:15], s[4:5], 0x30
	s_load_dwordx2 s[16:17], s[4:5], 0x28
	v_lshlrev_b32_e32 v2, 2, v37
	s_waitcnt lgkmcnt(0)
	global_load_dword v60, v2, s[14:15]
	global_load_dword v61, v2, s[14:15] offset:1024
	global_load_dword v62, v2, s[14:15] offset:2048
	global_load_dword v63, v2, s[14:15] offset:3072
	global_load_dword v64, v2, s[16:17]
	global_load_dword v65, v2, s[16:17] offset:1024
	global_load_dword v66, v2, s[16:17] offset:2048
	global_load_dword v67, v2, s[16:17] offset:3072
	s_add_u32 s16, s16, 0x1000
	s_addc_u32 s17, s17, 0
	global_load_dword v68, v2, s[16:17]
	global_load_dword v69, v2, s[16:17] offset:1024
	global_load_dword v70, v2, s[16:17] offset:2048
	global_load_dword v71, v2, s[16:17] offset:3072
	s_add_u32 s16, s16, 0x1000
	s_addc_u32 s17, s17, 0
	global_load_dword v72, v2, s[16:17]
	global_load_dword v73, v2, s[16:17] offset:1024
	global_load_dword v74, v2, s[16:17] offset:2048
	global_load_dword v75, v2, s[16:17] offset:3072
	s_add_u32 s16, s16, 0x1000
	s_addc_u32 s17, s17, 0
	global_load_dword v76, v2, s[16:17]
	global_load_dword v77, v2, s[16:17] offset:1024
	global_load_dword v78, v2, s[16:17] offset:2048
	global_load_dword v79, v2, s[16:17] offset:3072
	s_add_u32 s16, s16, 0x1000
	s_addc_u32 s17, s17, 0
	global_load_dword v80, v2, s[16:17]
	global_load_dword v81, v2, s[16:17] offset:1024
	global_load_dword v82, v2, s[16:17] offset:2048
	global_load_dword v83, v2, s[16:17] offset:3072
	s_add_u32 s16, s16, 0x1000
	s_addc_u32 s17, s17, 0
	global_load_dword v84, v2, s[16:17]
	global_load_dword v85, v2, s[16:17] offset:1024
	global_load_dword v86, v2, s[16:17] offset:2048
	global_load_dword v87, v2, s[16:17] offset:3072
	s_add_u32 s16, s16, 0x1000
	s_addc_u32 s17, s17, 0
	global_load_dword v88, v2, s[16:17]
	global_load_dword v89, v2, s[16:17] offset:1024
	global_load_dword v90, v2, s[16:17] offset:2048
	global_load_dword v91, v2, s[16:17] offset:3072
	s_add_u32 s16, s16, 0x1000
	s_addc_u32 s17, s17, 0
	global_load_dword v92, v2, s[16:17]
	global_load_dword v93, v2, s[16:17] offset:1024
	global_load_dword v94, v2, s[16:17] offset:2048
	global_load_dword v95, v2, s[16:17] offset:3072
	s_waitcnt vmcnt(35)
	v_mul_f32_e32 v1, 0xbfb8aa3b, v60
	v_exp_f32_e32 v1, v1
	s_nop 0
	v_add_f32_e32 v1, 1.0, v1
	v_div_scale_f32 v4, s[10:11], v1, v1, v60
	v_rcp_f32_e32 v5, v4
	s_nop 0
	v_fma_f32 v6, -v4, v5, 1.0
	v_fmac_f32_e32 v5, v6, v5
	v_div_scale_f32 v6, vcc, v60, v1, v60
	v_mul_f32_e32 v7, v6, v5
	v_fma_f32 v8, -v4, v7, v6
	v_fmac_f32_e32 v7, v8, v5
	v_fma_f32 v4, -v4, v7, v6
	v_div_fmas_f32 v4, v4, v5, v7
	v_div_fixup_f32 v0, v4, v1, v60
	ds_write_b32 v2, v0
	s_waitcnt vmcnt(34)
	v_mul_f32_e32 v1, 0xbfb8aa3b, v61
	v_exp_f32_e32 v1, v1
	s_nop 0
	v_add_f32_e32 v1, 1.0, v1
	v_div_scale_f32 v4, s[10:11], v1, v1, v61
	v_rcp_f32_e32 v5, v4
	s_nop 0
	v_fma_f32 v6, -v4, v5, 1.0
	v_fmac_f32_e32 v5, v6, v5
	v_div_scale_f32 v6, vcc, v61, v1, v61
	v_mul_f32_e32 v7, v6, v5
	v_fma_f32 v8, -v4, v7, v6
	v_fmac_f32_e32 v7, v8, v5
	v_fma_f32 v4, -v4, v7, v6
	v_div_fmas_f32 v4, v4, v5, v7
	v_div_fixup_f32 v0, v4, v1, v61
	ds_write_b32 v2, v0 offset:1024
	s_waitcnt vmcnt(33)
	v_mul_f32_e32 v1, 0xbfb8aa3b, v62
	v_exp_f32_e32 v1, v1
	s_nop 0
	v_add_f32_e32 v1, 1.0, v1
	v_div_scale_f32 v4, s[10:11], v1, v1, v62
	v_rcp_f32_e32 v5, v4
	s_nop 0
	v_fma_f32 v6, -v4, v5, 1.0
	v_fmac_f32_e32 v5, v6, v5
	v_div_scale_f32 v6, vcc, v62, v1, v62
	v_mul_f32_e32 v7, v6, v5
	v_fma_f32 v8, -v4, v7, v6
	v_fmac_f32_e32 v7, v8, v5
	v_fma_f32 v4, -v4, v7, v6
	v_div_fmas_f32 v4, v4, v5, v7
	v_div_fixup_f32 v0, v4, v1, v62
	ds_write_b32 v2, v0 offset:2048
	s_waitcnt vmcnt(32)
	v_mul_f32_e32 v1, 0xbfb8aa3b, v63
	v_exp_f32_e32 v1, v1
	s_nop 0
	v_add_f32_e32 v1, 1.0, v1
	v_div_scale_f32 v4, s[10:11], v1, v1, v63
	v_rcp_f32_e32 v5, v4
	s_nop 0
	v_fma_f32 v6, -v4, v5, 1.0
	v_fmac_f32_e32 v5, v6, v5
	v_div_scale_f32 v6, vcc, v63, v1, v63
	v_mul_f32_e32 v7, v6, v5
	v_fma_f32 v8, -v4, v7, v6
	v_fmac_f32_e32 v7, v8, v5
	v_fma_f32 v4, -v4, v7, v6
	v_div_fmas_f32 v4, v4, v5, v7
	v_div_fixup_f32 v0, v4, v1, v63
	ds_write_b32 v2, v0 offset:3072
	s_waitcnt vmcnt(31)
	v_mul_f32_e32 v1, 0xbfb8aa3b, v64
	v_exp_f32_e32 v1, v1
	s_nop 0
	v_add_f32_e32 v1, 1.0, v1
	v_div_scale_f32 v4, s[10:11], v1, v1, v64
	v_rcp_f32_e32 v5, v4
	s_nop 0
	v_fma_f32 v6, -v4, v5, 1.0
	v_fmac_f32_e32 v5, v6, v5
	v_div_scale_f32 v6, vcc, v64, v1, v64
	v_mul_f32_e32 v7, v6, v5
	v_fma_f32 v8, -v4, v7, v6
	v_fmac_f32_e32 v7, v8, v5
	v_fma_f32 v4, -v4, v7, v6
	v_div_fmas_f32 v4, v4, v5, v7
	v_div_fixup_f32 v0, v4, v1, v64
	ds_write_b32 v2, v0 offset:4096
	s_waitcnt vmcnt(30)
	v_mul_f32_e32 v1, 0xbfb8aa3b, v65
	v_exp_f32_e32 v1, v1
	s_nop 0
	v_add_f32_e32 v1, 1.0, v1
	v_div_scale_f32 v4, s[10:11], v1, v1, v65
	v_rcp_f32_e32 v5, v4
	s_nop 0
	v_fma_f32 v6, -v4, v5, 1.0
	v_fmac_f32_e32 v5, v6, v5
	v_div_scale_f32 v6, vcc, v65, v1, v65
	v_mul_f32_e32 v7, v6, v5
	v_fma_f32 v8, -v4, v7, v6
	v_fmac_f32_e32 v7, v8, v5
	v_fma_f32 v4, -v4, v7, v6
	v_div_fmas_f32 v4, v4, v5, v7
	v_div_fixup_f32 v0, v4, v1, v65
	ds_write_b32 v2, v0 offset:5120
	s_waitcnt vmcnt(29)
	v_mul_f32_e32 v1, 0xbfb8aa3b, v66
	v_exp_f32_e32 v1, v1
	s_nop 0
	v_add_f32_e32 v1, 1.0, v1
	v_div_scale_f32 v4, s[10:11], v1, v1, v66
	v_rcp_f32_e32 v5, v4
	s_nop 0
	v_fma_f32 v6, -v4, v5, 1.0
	v_fmac_f32_e32 v5, v6, v5
	v_div_scale_f32 v6, vcc, v66, v1, v66
	v_mul_f32_e32 v7, v6, v5
	v_fma_f32 v8, -v4, v7, v6
	v_fmac_f32_e32 v7, v8, v5
	v_fma_f32 v4, -v4, v7, v6
	v_div_fmas_f32 v4, v4, v5, v7
	v_div_fixup_f32 v0, v4, v1, v66
	ds_write_b32 v2, v0 offset:6144
	s_waitcnt vmcnt(28)
	v_mul_f32_e32 v1, 0xbfb8aa3b, v67
	v_exp_f32_e32 v1, v1
	s_nop 0
	v_add_f32_e32 v1, 1.0, v1
	v_div_scale_f32 v4, s[10:11], v1, v1, v67
	v_rcp_f32_e32 v5, v4
	s_nop 0
	v_fma_f32 v6, -v4, v5, 1.0
	v_fmac_f32_e32 v5, v6, v5
	v_div_scale_f32 v6, vcc, v67, v1, v67
	v_mul_f32_e32 v7, v6, v5
	v_fma_f32 v8, -v4, v7, v6
	v_fmac_f32_e32 v7, v8, v5
	v_fma_f32 v4, -v4, v7, v6
	v_div_fmas_f32 v4, v4, v5, v7
	v_div_fixup_f32 v0, v4, v1, v67
	ds_write_b32 v2, v0 offset:7168
	s_waitcnt vmcnt(27)
	v_mul_f32_e32 v1, 0xbfb8aa3b, v68
	v_exp_f32_e32 v1, v1
	s_nop 0
	v_add_f32_e32 v1, 1.0, v1
	v_div_scale_f32 v4, s[10:11], v1, v1, v68
	v_rcp_f32_e32 v5, v4
	s_nop 0
	v_fma_f32 v6, -v4, v5, 1.0
	v_fmac_f32_e32 v5, v6, v5
	v_div_scale_f32 v6, vcc, v68, v1, v68
	v_mul_f32_e32 v7, v6, v5
	v_fma_f32 v8, -v4, v7, v6
	v_fmac_f32_e32 v7, v8, v5
	v_fma_f32 v4, -v4, v7, v6
	v_div_fmas_f32 v4, v4, v5, v7
	v_div_fixup_f32 v0, v4, v1, v68
	ds_write_b32 v2, v0 offset:8192
	s_waitcnt vmcnt(26)
	v_mul_f32_e32 v1, 0xbfb8aa3b, v69
	v_exp_f32_e32 v1, v1
	s_nop 0
	v_add_f32_e32 v1, 1.0, v1
	v_div_scale_f32 v4, s[10:11], v1, v1, v69
	v_rcp_f32_e32 v5, v4
	s_nop 0
	v_fma_f32 v6, -v4, v5, 1.0
	v_fmac_f32_e32 v5, v6, v5
	v_div_scale_f32 v6, vcc, v69, v1, v69
	v_mul_f32_e32 v7, v6, v5
	v_fma_f32 v8, -v4, v7, v6
	v_fmac_f32_e32 v7, v8, v5
	v_fma_f32 v4, -v4, v7, v6
	v_div_fmas_f32 v4, v4, v5, v7
	v_div_fixup_f32 v0, v4, v1, v69
	ds_write_b32 v2, v0 offset:9216
	s_waitcnt vmcnt(25)
	v_mul_f32_e32 v1, 0xbfb8aa3b, v70
	v_exp_f32_e32 v1, v1
	s_nop 0
	v_add_f32_e32 v1, 1.0, v1
	v_div_scale_f32 v4, s[10:11], v1, v1, v70
	v_rcp_f32_e32 v5, v4
	s_nop 0
	v_fma_f32 v6, -v4, v5, 1.0
	v_fmac_f32_e32 v5, v6, v5
	v_div_scale_f32 v6, vcc, v70, v1, v70
	v_mul_f32_e32 v7, v6, v5
	v_fma_f32 v8, -v4, v7, v6
	v_fmac_f32_e32 v7, v8, v5
	v_fma_f32 v4, -v4, v7, v6
	v_div_fmas_f32 v4, v4, v5, v7
	v_div_fixup_f32 v0, v4, v1, v70
	ds_write_b32 v2, v0 offset:10240
	s_waitcnt vmcnt(24)
	v_mul_f32_e32 v1, 0xbfb8aa3b, v71
	v_exp_f32_e32 v1, v1
	s_nop 0
	v_add_f32_e32 v1, 1.0, v1
	v_div_scale_f32 v4, s[10:11], v1, v1, v71
	v_rcp_f32_e32 v5, v4
	s_nop 0
	v_fma_f32 v6, -v4, v5, 1.0
	v_fmac_f32_e32 v5, v6, v5
	v_div_scale_f32 v6, vcc, v71, v1, v71
	v_mul_f32_e32 v7, v6, v5
	v_fma_f32 v8, -v4, v7, v6
	v_fmac_f32_e32 v7, v8, v5
	v_fma_f32 v4, -v4, v7, v6
	v_div_fmas_f32 v4, v4, v5, v7
	v_div_fixup_f32 v0, v4, v1, v71
	ds_write_b32 v2, v0 offset:11264
	s_waitcnt vmcnt(23)
	v_mul_f32_e32 v1, 0xbfb8aa3b, v72
	v_exp_f32_e32 v1, v1
	s_nop 0
	v_add_f32_e32 v1, 1.0, v1
	v_div_scale_f32 v4, s[10:11], v1, v1, v72
	v_rcp_f32_e32 v5, v4
	s_nop 0
	v_fma_f32 v6, -v4, v5, 1.0
	v_fmac_f32_e32 v5, v6, v5
	v_div_scale_f32 v6, vcc, v72, v1, v72
	v_mul_f32_e32 v7, v6, v5
	v_fma_f32 v8, -v4, v7, v6
	v_fmac_f32_e32 v7, v8, v5
	v_fma_f32 v4, -v4, v7, v6
	v_div_fmas_f32 v4, v4, v5, v7
	v_div_fixup_f32 v0, v4, v1, v72
	ds_write_b32 v2, v0 offset:12288
	s_waitcnt vmcnt(22)
	v_mul_f32_e32 v1, 0xbfb8aa3b, v73
	v_exp_f32_e32 v1, v1
	s_nop 0
	v_add_f32_e32 v1, 1.0, v1
	v_div_scale_f32 v4, s[10:11], v1, v1, v73
	v_rcp_f32_e32 v5, v4
	s_nop 0
	v_fma_f32 v6, -v4, v5, 1.0
	v_fmac_f32_e32 v5, v6, v5
	v_div_scale_f32 v6, vcc, v73, v1, v73
	v_mul_f32_e32 v7, v6, v5
	v_fma_f32 v8, -v4, v7, v6
	v_fmac_f32_e32 v7, v8, v5
	v_fma_f32 v4, -v4, v7, v6
	v_div_fmas_f32 v4, v4, v5, v7
	v_div_fixup_f32 v0, v4, v1, v73
	ds_write_b32 v2, v0 offset:13312
	s_waitcnt vmcnt(21)
	v_mul_f32_e32 v1, 0xbfb8aa3b, v74
	v_exp_f32_e32 v1, v1
	s_nop 0
	v_add_f32_e32 v1, 1.0, v1
	v_div_scale_f32 v4, s[10:11], v1, v1, v74
	v_rcp_f32_e32 v5, v4
	s_nop 0
	v_fma_f32 v6, -v4, v5, 1.0
	v_fmac_f32_e32 v5, v6, v5
	v_div_scale_f32 v6, vcc, v74, v1, v74
	v_mul_f32_e32 v7, v6, v5
	v_fma_f32 v8, -v4, v7, v6
	v_fmac_f32_e32 v7, v8, v5
	v_fma_f32 v4, -v4, v7, v6
	v_div_fmas_f32 v4, v4, v5, v7
	v_div_fixup_f32 v0, v4, v1, v74
	ds_write_b32 v2, v0 offset:14336
	s_waitcnt vmcnt(20)
	v_mul_f32_e32 v1, 0xbfb8aa3b, v75
	v_exp_f32_e32 v1, v1
	s_nop 0
	v_add_f32_e32 v1, 1.0, v1
	v_div_scale_f32 v4, s[10:11], v1, v1, v75
	v_rcp_f32_e32 v5, v4
	s_nop 0
	v_fma_f32 v6, -v4, v5, 1.0
	v_fmac_f32_e32 v5, v6, v5
	v_div_scale_f32 v6, vcc, v75, v1, v75
	v_mul_f32_e32 v7, v6, v5
	v_fma_f32 v8, -v4, v7, v6
	v_fmac_f32_e32 v7, v8, v5
	v_fma_f32 v4, -v4, v7, v6
	v_div_fmas_f32 v4, v4, v5, v7
	v_div_fixup_f32 v0, v4, v1, v75
	ds_write_b32 v2, v0 offset:15360
	s_waitcnt vmcnt(19)
	v_mul_f32_e32 v1, 0xbfb8aa3b, v76
	v_exp_f32_e32 v1, v1
	s_nop 0
	v_add_f32_e32 v1, 1.0, v1
	v_div_scale_f32 v4, s[10:11], v1, v1, v76
	v_rcp_f32_e32 v5, v4
	s_nop 0
	v_fma_f32 v6, -v4, v5, 1.0
	v_fmac_f32_e32 v5, v6, v5
	v_div_scale_f32 v6, vcc, v76, v1, v76
	v_mul_f32_e32 v7, v6, v5
	v_fma_f32 v8, -v4, v7, v6
	v_fmac_f32_e32 v7, v8, v5
	v_fma_f32 v4, -v4, v7, v6
	v_div_fmas_f32 v4, v4, v5, v7
	v_div_fixup_f32 v0, v4, v1, v76
	ds_write_b32 v2, v0 offset:16384
	s_waitcnt vmcnt(18)
	v_mul_f32_e32 v1, 0xbfb8aa3b, v77
	v_exp_f32_e32 v1, v1
	s_nop 0
	v_add_f32_e32 v1, 1.0, v1
	v_div_scale_f32 v4, s[10:11], v1, v1, v77
	v_rcp_f32_e32 v5, v4
	s_nop 0
	v_fma_f32 v6, -v4, v5, 1.0
	v_fmac_f32_e32 v5, v6, v5
	v_div_scale_f32 v6, vcc, v77, v1, v77
	v_mul_f32_e32 v7, v6, v5
	v_fma_f32 v8, -v4, v7, v6
	v_fmac_f32_e32 v7, v8, v5
	v_fma_f32 v4, -v4, v7, v6
	v_div_fmas_f32 v4, v4, v5, v7
	v_div_fixup_f32 v0, v4, v1, v77
	ds_write_b32 v2, v0 offset:17408
	s_waitcnt vmcnt(17)
	v_mul_f32_e32 v1, 0xbfb8aa3b, v78
	v_exp_f32_e32 v1, v1
	s_nop 0
	v_add_f32_e32 v1, 1.0, v1
	v_div_scale_f32 v4, s[10:11], v1, v1, v78
	v_rcp_f32_e32 v5, v4
	s_nop 0
	v_fma_f32 v6, -v4, v5, 1.0
	v_fmac_f32_e32 v5, v6, v5
	v_div_scale_f32 v6, vcc, v78, v1, v78
	v_mul_f32_e32 v7, v6, v5
	v_fma_f32 v8, -v4, v7, v6
	v_fmac_f32_e32 v7, v8, v5
	v_fma_f32 v4, -v4, v7, v6
	v_div_fmas_f32 v4, v4, v5, v7
	v_div_fixup_f32 v0, v4, v1, v78
	ds_write_b32 v2, v0 offset:18432
	s_waitcnt vmcnt(16)
	v_mul_f32_e32 v1, 0xbfb8aa3b, v79
	v_exp_f32_e32 v1, v1
	s_nop 0
	v_add_f32_e32 v1, 1.0, v1
	v_div_scale_f32 v4, s[10:11], v1, v1, v79
	v_rcp_f32_e32 v5, v4
	s_nop 0
	v_fma_f32 v6, -v4, v5, 1.0
	v_fmac_f32_e32 v5, v6, v5
	v_div_scale_f32 v6, vcc, v79, v1, v79
	v_mul_f32_e32 v7, v6, v5
	v_fma_f32 v8, -v4, v7, v6
	v_fmac_f32_e32 v7, v8, v5
	v_fma_f32 v4, -v4, v7, v6
	v_div_fmas_f32 v4, v4, v5, v7
	v_div_fixup_f32 v0, v4, v1, v79
	ds_write_b32 v2, v0 offset:19456
	s_waitcnt vmcnt(15)
	v_mul_f32_e32 v1, 0xbfb8aa3b, v80
	v_exp_f32_e32 v1, v1
	s_nop 0
	v_add_f32_e32 v1, 1.0, v1
	v_div_scale_f32 v4, s[10:11], v1, v1, v80
	v_rcp_f32_e32 v5, v4
	s_nop 0
	v_fma_f32 v6, -v4, v5, 1.0
	v_fmac_f32_e32 v5, v6, v5
	v_div_scale_f32 v6, vcc, v80, v1, v80
	v_mul_f32_e32 v7, v6, v5
	v_fma_f32 v8, -v4, v7, v6
	v_fmac_f32_e32 v7, v8, v5
	v_fma_f32 v4, -v4, v7, v6
	v_div_fmas_f32 v4, v4, v5, v7
	v_div_fixup_f32 v0, v4, v1, v80
	ds_write_b32 v2, v0 offset:20480
	s_waitcnt vmcnt(14)
	v_mul_f32_e32 v1, 0xbfb8aa3b, v81
	v_exp_f32_e32 v1, v1
	s_nop 0
	v_add_f32_e32 v1, 1.0, v1
	v_div_scale_f32 v4, s[10:11], v1, v1, v81
	v_rcp_f32_e32 v5, v4
	s_nop 0
	v_fma_f32 v6, -v4, v5, 1.0
	v_fmac_f32_e32 v5, v6, v5
	v_div_scale_f32 v6, vcc, v81, v1, v81
	v_mul_f32_e32 v7, v6, v5
	v_fma_f32 v8, -v4, v7, v6
	v_fmac_f32_e32 v7, v8, v5
	v_fma_f32 v4, -v4, v7, v6
	v_div_fmas_f32 v4, v4, v5, v7
	v_div_fixup_f32 v0, v4, v1, v81
	ds_write_b32 v2, v0 offset:21504
	s_waitcnt vmcnt(13)
	v_mul_f32_e32 v1, 0xbfb8aa3b, v82
	v_exp_f32_e32 v1, v1
	s_nop 0
	v_add_f32_e32 v1, 1.0, v1
	v_div_scale_f32 v4, s[10:11], v1, v1, v82
	v_rcp_f32_e32 v5, v4
	s_nop 0
	v_fma_f32 v6, -v4, v5, 1.0
	v_fmac_f32_e32 v5, v6, v5
	v_div_scale_f32 v6, vcc, v82, v1, v82
	v_mul_f32_e32 v7, v6, v5
	v_fma_f32 v8, -v4, v7, v6
	v_fmac_f32_e32 v7, v8, v5
	v_fma_f32 v4, -v4, v7, v6
	v_div_fmas_f32 v4, v4, v5, v7
	v_div_fixup_f32 v0, v4, v1, v82
	ds_write_b32 v2, v0 offset:22528
	s_waitcnt vmcnt(12)
	v_mul_f32_e32 v1, 0xbfb8aa3b, v83
	v_exp_f32_e32 v1, v1
	s_nop 0
	v_add_f32_e32 v1, 1.0, v1
	v_div_scale_f32 v4, s[10:11], v1, v1, v83
	v_rcp_f32_e32 v5, v4
	s_nop 0
	v_fma_f32 v6, -v4, v5, 1.0
	v_fmac_f32_e32 v5, v6, v5
	v_div_scale_f32 v6, vcc, v83, v1, v83
	v_mul_f32_e32 v7, v6, v5
	v_fma_f32 v8, -v4, v7, v6
	v_fmac_f32_e32 v7, v8, v5
	v_fma_f32 v4, -v4, v7, v6
	v_div_fmas_f32 v4, v4, v5, v7
	v_div_fixup_f32 v0, v4, v1, v83
	ds_write_b32 v2, v0 offset:23552
	s_waitcnt vmcnt(11)
	v_mul_f32_e32 v1, 0xbfb8aa3b, v84
	v_exp_f32_e32 v1, v1
	s_nop 0
	v_add_f32_e32 v1, 1.0, v1
	v_div_scale_f32 v4, s[10:11], v1, v1, v84
	v_rcp_f32_e32 v5, v4
	s_nop 0
	v_fma_f32 v6, -v4, v5, 1.0
	v_fmac_f32_e32 v5, v6, v5
	v_div_scale_f32 v6, vcc, v84, v1, v84
	v_mul_f32_e32 v7, v6, v5
	v_fma_f32 v8, -v4, v7, v6
	v_fmac_f32_e32 v7, v8, v5
	v_fma_f32 v4, -v4, v7, v6
	v_div_fmas_f32 v4, v4, v5, v7
	v_div_fixup_f32 v0, v4, v1, v84
	ds_write_b32 v2, v0 offset:24576
	s_waitcnt vmcnt(10)
	v_mul_f32_e32 v1, 0xbfb8aa3b, v85
	v_exp_f32_e32 v1, v1
	s_nop 0
	v_add_f32_e32 v1, 1.0, v1
	v_div_scale_f32 v4, s[10:11], v1, v1, v85
	v_rcp_f32_e32 v5, v4
	s_nop 0
	v_fma_f32 v6, -v4, v5, 1.0
	v_fmac_f32_e32 v5, v6, v5
	v_div_scale_f32 v6, vcc, v85, v1, v85
	v_mul_f32_e32 v7, v6, v5
	v_fma_f32 v8, -v4, v7, v6
	v_fmac_f32_e32 v7, v8, v5
	v_fma_f32 v4, -v4, v7, v6
	v_div_fmas_f32 v4, v4, v5, v7
	v_div_fixup_f32 v0, v4, v1, v85
	ds_write_b32 v2, v0 offset:25600
	s_waitcnt vmcnt(9)
	v_mul_f32_e32 v1, 0xbfb8aa3b, v86
	v_exp_f32_e32 v1, v1
	s_nop 0
	v_add_f32_e32 v1, 1.0, v1
	v_div_scale_f32 v4, s[10:11], v1, v1, v86
	v_rcp_f32_e32 v5, v4
	s_nop 0
	v_fma_f32 v6, -v4, v5, 1.0
	v_fmac_f32_e32 v5, v6, v5
	v_div_scale_f32 v6, vcc, v86, v1, v86
	v_mul_f32_e32 v7, v6, v5
	v_fma_f32 v8, -v4, v7, v6
	v_fmac_f32_e32 v7, v8, v5
	v_fma_f32 v4, -v4, v7, v6
	v_div_fmas_f32 v4, v4, v5, v7
	v_div_fixup_f32 v0, v4, v1, v86
	ds_write_b32 v2, v0 offset:26624
	s_waitcnt vmcnt(8)
	v_mul_f32_e32 v1, 0xbfb8aa3b, v87
	v_exp_f32_e32 v1, v1
	s_nop 0
	v_add_f32_e32 v1, 1.0, v1
	v_div_scale_f32 v4, s[10:11], v1, v1, v87
	v_rcp_f32_e32 v5, v4
	s_nop 0
	v_fma_f32 v6, -v4, v5, 1.0
	v_fmac_f32_e32 v5, v6, v5
	v_div_scale_f32 v6, vcc, v87, v1, v87
	v_mul_f32_e32 v7, v6, v5
	v_fma_f32 v8, -v4, v7, v6
	v_fmac_f32_e32 v7, v8, v5
	v_fma_f32 v4, -v4, v7, v6
	v_div_fmas_f32 v4, v4, v5, v7
	v_div_fixup_f32 v0, v4, v1, v87
	ds_write_b32 v2, v0 offset:27648
	s_waitcnt vmcnt(7)
	v_mul_f32_e32 v1, 0xbfb8aa3b, v88
	v_exp_f32_e32 v1, v1
	s_nop 0
	v_add_f32_e32 v1, 1.0, v1
	v_div_scale_f32 v4, s[10:11], v1, v1, v88
	v_rcp_f32_e32 v5, v4
	s_nop 0
	v_fma_f32 v6, -v4, v5, 1.0
	v_fmac_f32_e32 v5, v6, v5
	v_div_scale_f32 v6, vcc, v88, v1, v88
	v_mul_f32_e32 v7, v6, v5
	v_fma_f32 v8, -v4, v7, v6
	v_fmac_f32_e32 v7, v8, v5
	v_fma_f32 v4, -v4, v7, v6
	v_div_fmas_f32 v4, v4, v5, v7
	v_div_fixup_f32 v0, v4, v1, v88
	ds_write_b32 v2, v0 offset:28672
	s_waitcnt vmcnt(6)
	v_mul_f32_e32 v1, 0xbfb8aa3b, v89
	v_exp_f32_e32 v1, v1
	s_nop 0
	v_add_f32_e32 v1, 1.0, v1
	v_div_scale_f32 v4, s[10:11], v1, v1, v89
	v_rcp_f32_e32 v5, v4
	s_nop 0
	v_fma_f32 v6, -v4, v5, 1.0
	v_fmac_f32_e32 v5, v6, v5
	v_div_scale_f32 v6, vcc, v89, v1, v89
	v_mul_f32_e32 v7, v6, v5
	v_fma_f32 v8, -v4, v7, v6
	v_fmac_f32_e32 v7, v8, v5
	v_fma_f32 v4, -v4, v7, v6
	v_div_fmas_f32 v4, v4, v5, v7
	v_div_fixup_f32 v0, v4, v1, v89
	ds_write_b32 v2, v0 offset:29696
	s_waitcnt vmcnt(5)
	v_mul_f32_e32 v1, 0xbfb8aa3b, v90
	v_exp_f32_e32 v1, v1
	s_nop 0
	v_add_f32_e32 v1, 1.0, v1
	v_div_scale_f32 v4, s[10:11], v1, v1, v90
	v_rcp_f32_e32 v5, v4
	s_nop 0
	v_fma_f32 v6, -v4, v5, 1.0
	v_fmac_f32_e32 v5, v6, v5
	v_div_scale_f32 v6, vcc, v90, v1, v90
	v_mul_f32_e32 v7, v6, v5
	v_fma_f32 v8, -v4, v7, v6
	v_fmac_f32_e32 v7, v8, v5
	v_fma_f32 v4, -v4, v7, v6
	v_div_fmas_f32 v4, v4, v5, v7
	v_div_fixup_f32 v0, v4, v1, v90
	ds_write_b32 v2, v0 offset:30720
	s_waitcnt vmcnt(4)
	v_mul_f32_e32 v1, 0xbfb8aa3b, v91
	v_exp_f32_e32 v1, v1
	s_nop 0
	v_add_f32_e32 v1, 1.0, v1
	v_div_scale_f32 v4, s[10:11], v1, v1, v91
	v_rcp_f32_e32 v5, v4
	s_nop 0
	v_fma_f32 v6, -v4, v5, 1.0
	v_fmac_f32_e32 v5, v6, v5
	v_div_scale_f32 v6, vcc, v91, v1, v91
	v_mul_f32_e32 v7, v6, v5
	v_fma_f32 v8, -v4, v7, v6
	v_fmac_f32_e32 v7, v8, v5
	v_fma_f32 v4, -v4, v7, v6
	v_div_fmas_f32 v4, v4, v5, v7
	v_div_fixup_f32 v0, v4, v1, v91
	ds_write_b32 v2, v0 offset:31744
	s_waitcnt vmcnt(3)
	v_mul_f32_e32 v1, 0xbfb8aa3b, v92
	v_exp_f32_e32 v1, v1
	s_nop 0
	v_add_f32_e32 v1, 1.0, v1
	v_div_scale_f32 v4, s[10:11], v1, v1, v92
	v_rcp_f32_e32 v5, v4
	s_nop 0
	v_fma_f32 v6, -v4, v5, 1.0
	v_fmac_f32_e32 v5, v6, v5
	v_div_scale_f32 v6, vcc, v92, v1, v92
	v_mul_f32_e32 v7, v6, v5
	v_fma_f32 v8, -v4, v7, v6
	v_fmac_f32_e32 v7, v8, v5
	v_fma_f32 v4, -v4, v7, v6
	v_div_fmas_f32 v4, v4, v5, v7
	v_div_fixup_f32 v0, v4, v1, v92
	ds_write_b32 v2, v0 offset:32768
	s_waitcnt vmcnt(2)
	v_mul_f32_e32 v1, 0xbfb8aa3b, v93
	v_exp_f32_e32 v1, v1
	s_nop 0
	v_add_f32_e32 v1, 1.0, v1
	v_div_scale_f32 v4, s[10:11], v1, v1, v93
	v_rcp_f32_e32 v5, v4
	s_nop 0
	v_fma_f32 v6, -v4, v5, 1.0
	v_fmac_f32_e32 v5, v6, v5
	v_div_scale_f32 v6, vcc, v93, v1, v93
	v_mul_f32_e32 v7, v6, v5
	v_fma_f32 v8, -v4, v7, v6
	v_fmac_f32_e32 v7, v8, v5
	v_fma_f32 v4, -v4, v7, v6
	v_div_fmas_f32 v4, v4, v5, v7
	v_div_fixup_f32 v0, v4, v1, v93
	ds_write_b32 v2, v0 offset:33792
	s_waitcnt vmcnt(1)
	v_mul_f32_e32 v1, 0xbfb8aa3b, v94
	v_exp_f32_e32 v1, v1
	s_nop 0
	v_add_f32_e32 v1, 1.0, v1
	v_div_scale_f32 v4, s[10:11], v1, v1, v94
	v_rcp_f32_e32 v5, v4
	s_nop 0
	v_fma_f32 v6, -v4, v5, 1.0
	v_fmac_f32_e32 v5, v6, v5
	v_div_scale_f32 v6, vcc, v94, v1, v94
	v_mul_f32_e32 v7, v6, v5
	v_fma_f32 v8, -v4, v7, v6
	v_fmac_f32_e32 v7, v8, v5
	v_fma_f32 v4, -v4, v7, v6
	v_div_fmas_f32 v4, v4, v5, v7
	v_div_fixup_f32 v0, v4, v1, v94
	ds_write_b32 v2, v0 offset:34816
	s_waitcnt vmcnt(0)
	v_mul_f32_e32 v1, 0xbfb8aa3b, v95
	v_exp_f32_e32 v1, v1
	s_nop 0
	v_add_f32_e32 v1, 1.0, v1
	v_div_scale_f32 v4, s[10:11], v1, v1, v95
	v_rcp_f32_e32 v5, v4
	s_nop 0
	v_fma_f32 v6, -v4, v5, 1.0
	v_fmac_f32_e32 v5, v6, v5
	v_div_scale_f32 v6, vcc, v95, v1, v95
	v_mul_f32_e32 v7, v6, v5
	v_fma_f32 v8, -v4, v7, v6
	v_fmac_f32_e32 v7, v8, v5
	v_fma_f32 v4, -v4, v7, v6
	v_div_fmas_f32 v4, v4, v5, v7
	v_div_fixup_f32 v0, v4, v1, v95
	ds_write_b32 v2, v0 offset:35840
